# grid barriers inside a layer replaced by an XCD-local counter barrier (workgroups remapped by hardware XCC id so every in-layer dependency stays inside one XCD; falls back to the full hierarchical bar
# speedup vs baseline: 1.0457x; 1.0252x over previous
; __global__ void __launch_bounds__(NTHREADS) fwd_megakernel(Params p) {
;     extern __shared__ __attribute__((aligned(16))) char lds[];
;     if (p.never) cg::this_grid().sync();
_Z14fwd_megakernel6Params:
	s_mov_b32 s84, s2
	s_mov_b32 s99, 0
	v_writelane_b32 v254, s0, 0
	v_and_b32_e32 v245, 0x3ff, v0
	s_nop 0
	v_writelane_b32 v254, s1, 1
	s_load_dword s0, s[0:1], 0xb0
	s_waitcnt lgkmcnt(0)
	s_cmp_lg_u32 s0, 0
	s_cbranch_scc0 .LBB0_12
	v_and_b32_e32 v0, 0x3fffffff, v0
	v_cmp_eq_u32_e32 vcc, 0, v0
	s_barrier
	s_and_saveexec_b64 s[0:1], vcc
	s_cbranch_execz .LBB0_11
	v_readlane_b32 s2, v254, 0
	v_readlane_b32 s3, v254, 1
	buffer_wbl2 sc1
	s_load_dwordx2 s[2:3], s[2:3], 0x110
	s_mov_b64 s[4:5], exec
	v_mbcnt_lo_u32_b32 v0, s4, 0
	v_mbcnt_hi_u32_b32 v0, s5, v0
	v_cmp_eq_u32_e32 vcc, 0, v0
	s_waitcnt lgkmcnt(0)
	s_load_dword s8, s[2:3], 0x28
	s_and_saveexec_b64 s[6:7], vcc
	s_cbranch_execz .LBB0_4
	s_bcnt1_i32_b64 s4, s[4:5]
	v_mov_b32_e32 v1, 0
	v_mov_b32_e32 v2, s4
	global_atomic_add v1, v1, v2, s[2:3] offset:32 sc0

; #define LAS __attribute__((address_space(3)))
; __device__ __forceinline__ unsigned xb_add(unsigned* p, unsigned v) { return __hip_atomic_fetch_add(p, v, __ATOMIC_RELAXED, __HIP_MEMORY_SCOPE_AGENT); }
; __device__ __forceinline__ unsigned xb_xcc_id() { return (unsigned)__builtin_amdgcn_s_getreg((3 << 11) | 20) & 0xFu; }
; __device__ __forceinline__ XcdBarrier xcd_barrier_post(unsigned* bar, volatile LAS unsigned* st) {
;     XcdBarrier b; b.bar = bar; b.x = xb_xcc_id(); b.st = st;
;     if (threadIdx.x == 0) (void)xb_add(&bar[XB_XCNT(b.x)], 1u);
;     return b;
; __global__ void __launch_bounds__(NTHREADS) fwd_megakernel(Params p) {
;     ...
;     volatile LAS unsigned* st = (volatile LAS unsigned*)(lds + LDS_PHASE_BYTES);
;     if (threadIdx.x < 4) st[threadIdx.x] = 0u;
;     __syncthreads();
;     const XcdBarrier gb = xcd_barrier_post(p.bar, st);
.LBB0_12:
	v_cmp_gt_u32_e32 vcc, 4, v245
	s_and_saveexec_b64 s[0:1], vcc
	v_lshl_add_u32 v0, v245, 2, 0
	v_add_u32_e32 v0, 0x23000, v0
	v_mov_b32_e32 v1, 0
	ds_write_b32 v0, v1
	s_or_b64 exec, exec, s[0:1]
	v_readlane_b32 s0, v254, 0
	v_readlane_b32 s1, v254, 1
	s_load_dwordx2 s[82:83], s[0:1], 0x98
	s_waitcnt lgkmcnt(0)
	s_barrier
	s_getreg_b32 s0, hwreg(HW_REG_XCC_ID, 0, 4)
	s_and_b32 s0, s0, 15
	v_writelane_b32 v254, s0, 2
	v_cmp_eq_u32_e64 s[66:67], 0, v245
	s_and_saveexec_b64 s[0:1], s[66:67]
	s_cbranch_execz .LBB0_17
	s_mov_b64 s[2:3], exec
	v_mbcnt_lo_u32_b32 v0, s2, 0
	v_mbcnt_hi_u32_b32 v0, s3, v0
	v_cmp_eq_u32_e32 vcc, 0, v0
	s_and_b64 s[4:5], exec, vcc
	s_mov_b64 exec, s[4:5]
	s_cbranch_execz .LBB0_17
	v_readlane_b32 s4, v254, 2
	s_lshl_b32 s4, s4, 8
	s_bcnt1_i32_b64 s2, s[2:3]
	v_mov_b32_e32 v0, s4
	v_mov_b32_e32 v1, s2
	global_atomic_add v0, v0, v1, s[82:83] offset:1024 sc0
	v_mov_b32_e32 v1, 0x23010
	s_waitcnt vmcnt(0)
	ds_write_b32 v1, v0
	s_waitcnt lgkmcnt(0)

; __device__ __forceinline__ void xcd_barrier(const XcdBarrier& b) {
;     ...
;     }
;     __syncthreads();
.LBB0_99:
	s_or_b64 exec, exec, s[0:1]
	s_mov_b64 s[0:1], src_shared_base
	v_writelane_b32 v254, s0, 4
	s_waitcnt lgkmcnt(0)
	s_barrier
; #define PG8_LAS __attribute__((address_space(3)))
; __global__ void __launch_bounds__(NTHREADS) fwd_megakernel(Params p) {
;     ...
;     const XcdBarrier gb = xcd_barrier_post(p.bar, st);
;     prologue_phase(lds, p);
;     xcd_barrier(gb);
;     for (int layer = 0; layer < DEPTH; ++layer) {
;         for (int rep = 0; rep < REP_GEMM0; ++rep) {
;         { pg8::Gemm g{p.xb, p.wi_t + (size_t)layer * 4096 * 1024, NTOK, IN_W, 1024}; pg8::StaticOrder S; S.init(NTOK, IN_W, (int)gridDim.x, (int)blockIdx.x);
;           pg8::EpiZ E{p.z, p.vT, p.rss};
;           pg8::gemm_phase<pg8::EpiZ, pg8::StaticOrder, true, true>((PG8_LAS unsigned char*)lds, g, S, E); }
	v_writelane_b32 v254, s1, 5
	s_nop 0
	v_readlane_b32 s12, v254, 0
	v_readlane_b32 s13, v254, 1
	v_and_b32_e32 v3, 15, v245
	v_lshlrev_b32_e32 v0, 8, v3
	global_load_dword v1, v0, s[82:83] offset:1024 sc1
	v_mov_b32_e32 v2, 0x23010
	ds_read_b32 v2, v2
	v_cmp_gt_u32_e32 vcc, 8, v3
	s_nop 1
	v_cndmask_b32_e64 v3, 0, 32, vcc
	v_readlane_b32 s1, v254, 2
	s_waitcnt vmcnt(0) lgkmcnt(0)
	v_readfirstlane_b32 s0, v2
	v_cmp_ne_u32_e32 vcc, v1, v3
	s_lshl_b32 s0, s0, 3
	s_add_i32 s0, s0, s1
	s_cmp_eq_u64 vcc, 0
	s_cselect_b32 s84, s0, s84
	s_cselect_b32 s99, 1, 0
	s_load_dword s0, s[12:13], 0xb8
	s_load_dwordx16 s[48:63], s[12:13], 0x58
	s_add_u32 s64, s12, 0xb8
	s_addc_u32 s65, s13, 0
	s_mov_b32 s71, 0
	s_waitcnt lgkmcnt(0)
	v_writelane_b32 v254, s0, 6
	s_ashr_i32 s0, s0, 31
	s_cmpk_lt_i32 s84, 0x400
	v_writelane_b32 v254, s0, 7
	s_cselect_b64 s[0:1], -1, 0
	v_writelane_b32 v254, s0, 8
	s_ashr_i32 s90, s84, 31
	v_mov_b32_e32 v153, 0
	v_writelane_b32 v254, s1, 9
	s_lshr_b32 s0, s90, 29
	s_add_i32 s0, s84, s0
	s_ashr_i32 s3, s0, 3
	s_and_b32 s0, s0, -8
	s_sub_i32 s2, s84, s0
	s_lshl_b32 s4, s2, 7
	s_add_u32 s68, s60, 0x1000000
	s_addc_u32 s69, s61, 0
	s_add_u32 s76, s58, 0x2000000
	s_addc_u32 s77, s59, 0
	s_add_u32 s72, s82, 0x200
	s_addc_u32 s73, s83, 0
	s_add_u32 s74, s82, 0x1000
	s_addc_u32 s75, s83, 0
	s_add_u32 s78, s82, 0x1100
	s_addc_u32 s79, s83, 0
	s_add_u32 s80, s82, 0x1200
	s_addc_u32 s81, s83, 0
	s_add_u32 s92, s82, 0x1300
	s_addc_u32 s93, s83, 0
	s_add_u32 s0, s82, 0x3400
	s_addc_u32 s1, s83, 0
	v_writelane_b32 v254, s0, 10
	v_mov_b32_e32 v238, 1
	v_mov_b32_e32 v251, 0x41000000
	v_writelane_b32 v254, s1, 11
	s_add_u32 s0, s82, 0x3500
	s_addc_u32 s1, s83, 0
	v_writelane_b32 v254, s0, 12
	s_cmpk_lt_i32 s84, 0x300
	v_mov_b32_e32 v236, 0x358637bd
	v_writelane_b32 v254, s1, 13
	s_cselect_b64 s[0:1], -1, 0
	v_writelane_b32 v254, s0, 14
	v_mov_b64_e32 v[246:247], 0x3ff
	v_mbcnt_hi_u32_b32 v240, -1, v8
	v_writelane_b32 v254, s1, 15
	s_add_u32 s0, s58, 0x3000000
	s_addc_u32 s1, s59, 0
	v_writelane_b32 v254, s0, 16
	v_mov_b32_e32 v155, 0x7cf
	v_mov_b32_e32 v243, 0xf149f2ca
	v_writelane_b32 v254, s1, 17
	s_add_u32 s0, s58, 0x1000000
	v_writelane_b32 v254, s0, 18
	s_addc_u32 s0, s59, 0
	v_writelane_b32 v254, s0, 19
	s_add_u32 s0, s58, 0x4000000
	s_addc_u32 s1, s59, 0
	v_writelane_b32 v254, s0, 20
	s_cmpk_gt_i32 s84, 0x2ff
	s_movk_i32 s47, 0x2000
	v_writelane_b32 v254, s1, 21
	s_cselect_b64 s[0:1], -1, 0
	s_cmpk_lt_i32 s84, 0x100
	s_cselect_b64 s[6:7], -1, 0
	v_writelane_b32 v254, s6, 22
	s_lshl_b32 s5, s2, 5
	s_cmp_lt_i32 s2, 0
	v_writelane_b32 v254, s7, 23
	s_mul_i32 s6, s2, 0x81
	s_mul_i32 s2, s2, 33
	s_cselect_b32 s4, s6, s4
	s_cselect_b32 s5, s2, s5
	s_add_i32 s2, s4, s3
	s_ashr_i32 s4, s2, 31
	s_lshr_b32 s4, s4, 25
	s_add_i32 s4, s2, s4
	s_ashr_i32 s6, s4, 7
	s_and_b32 s4, s4, 0xff80
	s_sub_i32 s4, s2, s4
	s_bfe_i32 s2, s4, 0x80000
	s_bfe_u32 s2, s2, 0x3000c
	s_add_i32 s7, s4, s2
	s_bfe_i32 s2, s7, 0x80000
	s_and_b32 s7, s7, 0xf8
	s_sub_i32 s4, s4, s7
	s_lshl_b32 s6, s6, 3
	s_sext_i32_i16 s8, s2
	s_sext_i32_i8 s4, s4
	s_add_i32 s14, s6, s4
	s_ashr_i32 s4, s8, 3
	s_add_i32 s3, s5, s3
	v_writelane_b32 v254, s4, 24
	s_ashr_i32 s4, s3, 31
	s_lshr_b32 s4, s4, 27
	s_add_i32 s4, s3, s4
	s_ashr_i32 s5, s4, 5
	s_and_b32 s4, s4, 0xffe0
	s_sub_i32 s3, s3, s4
	s_bfe_i32 s4, s3, 0x80000
	s_bfe_u32 s4, s4, 0x3000c
	s_add_i32 s4, s3, s4
	s_bfe_i32 s6, s4, 0x80000
	s_and_b32 s4, s4, 0xf8
	s_sub_i32 s3, s3, s4
	s_lshl_b32 s5, s5, 3
	s_sext_i32_i16 s6, s6
	s_sext_i32_i8 s3, s3
	s_lshr_b32 s2, s8, 3
	s_add_i32 s8, s5, s3
	s_ashr_i32 s3, s6, 3
	v_writelane_b32 v254, s3, 25
	s_mov_b32 s4, s14
	v_writelane_b32 v254, s4, 26
	s_bfe_i64 s[2:3], s[2:3], 0x100000
	s_ashr_i32 s15, s14, 31
	v_writelane_b32 v254, s5, 27
	s_lshl_b64 s[2:3], s[2:3], 19
	s_lshr_b32 s10, s6, 3
	s_lshl_b64 s[4:5], s[14:15], 19
	v_writelane_b32 v254, s2, 28
	s_mov_b32 s96, 0x800000
	s_mov_b32 s97, 0xffff
	v_writelane_b32 v254, s3, 29
	s_add_u32 s2, s54, s4
	s_addc_u32 s3, s55, s5
	s_add_u32 s4, s2, 0x40000
	v_writelane_b32 v254, s2, 30
	s_addc_u32 s5, s3, 0
	s_ashr_i32 s9, s8, 31
	v_writelane_b32 v254, s3, 31
	v_writelane_b32 v254, s4, 32
	s_mov_b32 s2, s10
	s_mov_b32 s91, 0x7149f2ca
	v_writelane_b32 v254, s5, 33
	v_writelane_b32 v254, s2, 34
	s_mov_b64 s[94:95], 0x80
	s_mov_b32 s20, 0x3fb8aa3b
	v_writelane_b32 v254, s3, 35
	s_bfe_i64 s[2:3], s[10:11], 0x100000
	s_lshl_b64 s[2:3], s[2:3], 19
	v_writelane_b32 v254, s2, 36
	s_mov_b64 s[88:89], s[76:77]
	s_nop 0
	v_writelane_b32 v254, s3, 37
	v_writelane_b32 v254, s8, 38
	s_lshl_b64 s[2:3], s[8:9], 19
	s_add_u32 s2, s62, s2
	v_writelane_b32 v254, s9, 39
	s_addc_u32 s3, s63, s3
	s_add_u32 s4, s2, 0x40000
	v_writelane_b32 v254, s2, 40
	s_addc_u32 s5, s3, 0
	s_xor_b64 s[0:1], s[0:1], -1
	v_writelane_b32 v254, s3, 41
	v_writelane_b32 v254, s4, 42
	s_nop 1
	v_writelane_b32 v254, s5, 43
	v_writelane_b32 v254, s0, 44
	s_nop 1
	v_writelane_b32 v254, s1, 45
	s_add_i32 s0, 0, 0x23000
	v_writelane_b32 v254, s0, 46
	s_add_i32 s0, 0, 0x23004
	v_writelane_b32 v254, s0, 47
	s_add_i32 s0, 0, 0x23090
	v_writelane_b32 v254, s0, 48
	s_add_i32 s0, 0, 0x23890
	v_writelane_b32 v254, s0, 49
	s_add_i32 s0, 0, 0x11800
	v_writelane_b32 v254, s0, 50
	s_add_i32 s0, 0, 0x1e800
	v_writelane_b32 v254, s0, 51
	s_load_dwordx4 s[0:3], s[12:13], 0x40
	s_waitcnt lgkmcnt(0)
	v_writelane_b32 v254, s0, 52
	s_nop 1
	v_writelane_b32 v254, s1, 53
	v_writelane_b32 v254, s2, 54
	v_writelane_b32 v254, s3, 55
	s_mov_b64 s[0:1], s[2:3]
	v_writelane_b32 v254, s0, 56
	s_nop 1
	v_writelane_b32 v254, s1, 57
	s_mov_b32 s0, s71
	v_writelane_b32 v254, s0, 58
	s_nop 1
	v_writelane_b32 v254, s1, 59
	s_load_dwordx8 s[0:7], s[12:13], 0x20
	s_waitcnt lgkmcnt(0)
	v_writelane_b32 v254, s0, 60
	s_nop 1
	v_writelane_b32 v255, s4, 0
	v_writelane_b32 v255, s5, 1
	v_writelane_b32 v255, s6, 2
	v_writelane_b32 v255, s7, 3
	v_writelane_b32 v255, s48, 4
	v_writelane_b32 v254, s1, 61
	v_writelane_b32 v254, s2, 62
	v_writelane_b32 v255, s49, 5
	v_writelane_b32 v255, s50, 6
	v_writelane_b32 v255, s51, 7
	v_writelane_b32 v255, s52, 8
	v_writelane_b32 v255, s53, 9
	v_writelane_b32 v255, s54, 10
	v_writelane_b32 v255, s55, 11
	v_writelane_b32 v255, s56, 12
	v_writelane_b32 v255, s57, 13
	v_writelane_b32 v255, s58, 14
	v_writelane_b32 v255, s59, 15
	v_writelane_b32 v255, s60, 16
	v_writelane_b32 v255, s61, 17
	v_writelane_b32 v255, s62, 18
	v_writelane_b32 v255, s63, 19
	v_writelane_b32 v255, s64, 20
	v_writelane_b32 v254, s3, 63
	s_nop 0
	v_writelane_b32 v255, s65, 21
	v_writelane_b32 v255, s68, 22
	s_nop 1
	v_writelane_b32 v255, s69, 23
	v_writelane_b32 v255, s66, 24
	s_nop 1
	v_writelane_b32 v255, s67, 25
	v_writelane_b32 v255, s72, 26
	s_nop 1
	v_writelane_b32 v255, s73, 27
	v_writelane_b32 v255, s74, 28
	s_nop 1
	v_writelane_b32 v255, s75, 29
	v_writelane_b32 v255, s78, 30
	s_nop 1
	v_writelane_b32 v255, s79, 31
	v_writelane_b32 v255, s80, 32
	s_nop 1
	v_writelane_b32 v255, s81, 33
	v_writelane_b32 v255, s92, 34
	s_nop 1
	v_writelane_b32 v255, s93, 35
	s_branch .LBB0_103

; __device__ __forceinline__ unsigned xb_ld(unsigned* p)              { return __hip_atomic_load(p, __ATOMIC_RELAXED, __HIP_MEMORY_SCOPE_AGENT); }
; __device__ __forceinline__ unsigned xb_add(unsigned* p, unsigned v) { return __hip_atomic_fetch_add(p, v, __ATOMIC_RELAXED, __HIP_MEMORY_SCOPE_AGENT); }
; #define XB_SPIN(cond, bar) do { unsigned _sp = 0; while (cond) { __builtin_amdgcn_s_sleep(1); \
;     if ((++_sp & 255u) == 0u) { if (xb_ld(&(bar)[XB_TMO])) break; if (_sp > XB_SPIN_CAP) { atomicAdd(&(bar)[XB_TMO], 1u); break; } } } } while (0)
; __device__ __forceinline__ void xcd_barrier(const XcdBarrier& b) {
;     asm volatile("s_waitcnt vmcnt(0)" ::: "memory");
;     __syncthreads();
;     if (threadIdx.x == 0) {
;         unsigned* bar = b.bar;
;         unsigned bx = b.x; asm volatile("" : "+s"(bx));
;         __builtin_amdgcn_s_waitcnt(0);
;         unsigned nloc = b.st[0], nx = b.st[1];
;         if (nloc == 0u) { xcd_barrier_complete(bar, bx, nloc, nx); b.st[0] = nloc; b.st[1] = nx; }
;         const unsigned old = xb_add(&bar[XB_XSUB(bx)], 1u);
;         const unsigned gen = old / nloc;
;         if (old + 1u == (gen + 1u) * nloc) {
;             __builtin_amdgcn_fence(__ATOMIC_RELEASE, "agent");
;             asm volatile("s_waitcnt vmcnt(0)" ::: "memory");
;             const unsigned og = xb_add(&bar[XB_TOP], 1u);
;             const unsigned tg = og / nx;
;             if (og + 1u == (tg + 1u) * nx) xb_add(&bar[XB_TOPGEN], 1u);
;             else XB_SPIN(xb_ld(&bar[XB_TOPGEN]) == tg, bar);
;             __builtin_amdgcn_fence(__ATOMIC_ACQUIRE, "agent");
;             xb_add(&bar[XB_XGEN(bx)], 1u);
;             asm volatile("s_waitcnt vmcnt(0)" ::: "memory");
;         } else {
;             XB_SPIN(xb_ld(&bar[XB_XGEN(bx)]) == gen, bar);
;             __builtin_amdgcn_fence(__ATOMIC_ACQUIRE, "agent");
;             asm volatile("s_waitcnt vmcnt(0)" ::: "memory");
;         }
;     }
;     __syncthreads();
.LBB0_379:
	s_waitcnt vmcnt(0)
	s_waitcnt vmcnt(63) expcnt(7) lgkmcnt(15)
	s_barrier
	s_and_saveexec_b64 s[0:1], s[66:67]
	s_cbranch_execz .LBB0_431
	s_cmp_eq_u32 s99, 0
	s_cbranch_scc1 .Lxb_full_1
	v_readlane_b32 s2, v254, 2
	v_mov_b32_e32 v1, 1
	s_lshl_b32 s2, s2, 8
	s_mov_b32 s98, 0
	v_mov_b32_e32 v0, s2
	global_atomic_add v1, v0, v1, s[82:83] offset:1152 sc0
	s_waitcnt vmcnt(0)
	v_lshrrev_b32_e32 v1, 5, v1
	v_add_u32_e32 v1, 1, v1
	v_lshlrev_b32_e32 v1, 5, v1
.Lxb_spin_1:
	global_load_dword v2, v0, s[82:83] offset:1152 sc1
	s_add_u32 s98, s98, 1
	s_waitcnt vmcnt(0)
	v_cmp_lt_u32_e32 vcc, v2, v1
	s_cbranch_vccz .Lxb_done_1
	s_cmp_lt_u32 s98, 0x100000
	s_cbranch_scc0 .Lxb_done_1
	s_sleep 1
	s_branch .Lxb_spin_1
.Lxb_done_1:
	buffer_inv sc1
	s_waitcnt vmcnt(0)
	s_branch .LBB0_431
.Lxb_full_1:
	v_readlane_b32 s2, v254, 46
	v_readlane_b32 s8, v254, 2
	s_waitcnt vmcnt(0) expcnt(0) lgkmcnt(0)
	v_mov_b32_e32 v0, s2
	ds_read_b32 v2, v0
	v_readlane_b32 s2, v254, 47
	s_waitcnt lgkmcnt(0)
	v_cmp_ne_u32_e32 vcc, 0, v2
	v_mov_b32_e32 v0, s2
	ds_read_b32 v0, v0
	s_cbranch_vccnz .LBB0_395
	s_load_dwordx2 s[2:3], s[64:65], 0x4
	v_readlane_b32 s4, v254, 6
	s_mov_b32 s10, 1
	s_waitcnt lgkmcnt(0)
	s_mul_i32 s9, s2, s4
	s_mul_i32 s9, s9, s3
	s_branch .LBB0_383

; __device__ __forceinline__ unsigned xb_ld(unsigned* p)              { return __hip_atomic_load(p, __ATOMIC_RELAXED, __HIP_MEMORY_SCOPE_AGENT); }
; __device__ __forceinline__ unsigned xb_add(unsigned* p, unsigned v) { return __hip_atomic_fetch_add(p, v, __ATOMIC_RELAXED, __HIP_MEMORY_SCOPE_AGENT); }
; #define XB_SPIN(cond, bar) do { unsigned _sp = 0; while (cond) { __builtin_amdgcn_s_sleep(1); \
;     if ((++_sp & 255u) == 0u) { if (xb_ld(&(bar)[XB_TMO])) break; if (_sp > XB_SPIN_CAP) { atomicAdd(&(bar)[XB_TMO], 1u); break; } } } } while (0)
; __device__ __forceinline__ void xcd_barrier(const XcdBarrier& b) {
;     asm volatile("s_waitcnt vmcnt(0)" ::: "memory");
;     __syncthreads();
;     if (threadIdx.x == 0) {
;         unsigned* bar = b.bar;
;         unsigned bx = b.x; asm volatile("" : "+s"(bx));
;         __builtin_amdgcn_s_waitcnt(0);
;         unsigned nloc = b.st[0], nx = b.st[1];
;         if (nloc == 0u) { xcd_barrier_complete(bar, bx, nloc, nx); b.st[0] = nloc; b.st[1] = nx; }
;         const unsigned old = xb_add(&bar[XB_XSUB(bx)], 1u);
;         const unsigned gen = old / nloc;
;         if (old + 1u == (gen + 1u) * nloc) {
;             __builtin_amdgcn_fence(__ATOMIC_RELEASE, "agent");
;             asm volatile("s_waitcnt vmcnt(0)" ::: "memory");
;             const unsigned og = xb_add(&bar[XB_TOP], 1u);
;             const unsigned tg = og / nx;
;             if (og + 1u == (tg + 1u) * nx) xb_add(&bar[XB_TOPGEN], 1u);
;             else XB_SPIN(xb_ld(&bar[XB_TOPGEN]) == tg, bar);
;             __builtin_amdgcn_fence(__ATOMIC_ACQUIRE, "agent");
;             xb_add(&bar[XB_XGEN(bx)], 1u);
;             asm volatile("s_waitcnt vmcnt(0)" ::: "memory");
;         } else {
;             XB_SPIN(xb_ld(&bar[XB_XGEN(bx)]) == gen, bar);
; __global__ void __launch_bounds__(NTHREADS) fwd_megakernel(Params p) {
;     ...
;         xcd_barrier(gb);
.LBB0_547:
	s_or_b64 exec, exec, s[76:77]
	s_waitcnt vmcnt(0)
	v_readlane_b32 s66, v255, 24
	v_readlane_b32 s67, v255, 25
	s_barrier
	s_and_saveexec_b64 s[0:1], s[66:67]
	v_readlane_b32 s72, v255, 26
	v_readlane_b32 s74, v255, 28
	v_readlane_b32 s78, v255, 30
	v_readlane_b32 s80, v255, 32
	v_readlane_b32 s92, v255, 34
	v_readlane_b32 s73, v255, 27
	v_readlane_b32 s75, v255, 29
	v_readlane_b32 s79, v255, 31
	v_readlane_b32 s81, v255, 33
	v_readlane_b32 s93, v255, 35
	s_cbranch_execz .LBB0_599
	s_cmp_eq_u32 s99, 0
	s_cbranch_scc1 .Lxb_full_2
	v_readlane_b32 s2, v254, 2
	v_mov_b32_e32 v1, 1
	s_lshl_b32 s2, s2, 8
	s_mov_b32 s98, 0
	v_mov_b32_e32 v0, s2
	global_atomic_add v1, v0, v1, s[82:83] offset:1152 sc0
	s_waitcnt vmcnt(0)
	v_lshrrev_b32_e32 v1, 5, v1
	v_add_u32_e32 v1, 1, v1
	v_lshlrev_b32_e32 v1, 5, v1

; __device__ __forceinline__ unsigned xb_ld(unsigned* p)              { return __hip_atomic_load(p, __ATOMIC_RELAXED, __HIP_MEMORY_SCOPE_AGENT); }
; __device__ __forceinline__ unsigned xb_add(unsigned* p, unsigned v) { return __hip_atomic_fetch_add(p, v, __ATOMIC_RELAXED, __HIP_MEMORY_SCOPE_AGENT); }
; #define XB_SPIN(cond, bar) do { unsigned _sp = 0; while (cond) { __builtin_amdgcn_s_sleep(1); \
;     if ((++_sp & 255u) == 0u) { if (xb_ld(&(bar)[XB_TMO])) break; if (_sp > XB_SPIN_CAP) { atomicAdd(&(bar)[XB_TMO], 1u); break; } } } } while (0)
; __device__ __forceinline__ void xcd_barrier(const XcdBarrier& b) {
;     ...
;     if (threadIdx.x == 0) {
;         unsigned* bar = b.bar;
;         unsigned bx = b.x; asm volatile("" : "+s"(bx));
;         __builtin_amdgcn_s_waitcnt(0);
;         unsigned nloc = b.st[0], nx = b.st[1];
;         if (nloc == 0u) { xcd_barrier_complete(bar, bx, nloc, nx); b.st[0] = nloc; b.st[1] = nx; }
;         const unsigned old = xb_add(&bar[XB_XSUB(bx)], 1u);
;         const unsigned gen = old / nloc;
;         if (old + 1u == (gen + 1u) * nloc) {
;             __builtin_amdgcn_fence(__ATOMIC_RELEASE, "agent");
;             asm volatile("s_waitcnt vmcnt(0)" ::: "memory");
;             const unsigned og = xb_add(&bar[XB_TOP], 1u);
;             const unsigned tg = og / nx;
;             if (og + 1u == (tg + 1u) * nx) xb_add(&bar[XB_TOPGEN], 1u);
;             else XB_SPIN(xb_ld(&bar[XB_TOPGEN]) == tg, bar);
.Lxb_full_2:
	v_readlane_b32 s2, v254, 46
	v_readlane_b32 s8, v254, 2
	s_waitcnt vmcnt(0) expcnt(0) lgkmcnt(0)
	v_mov_b32_e32 v0, s2
	ds_read_b32 v2, v0
	v_readlane_b32 s2, v254, 47
	s_waitcnt lgkmcnt(0)
	v_cmp_ne_u32_e32 vcc, 0, v2
	v_mov_b32_e32 v0, s2
	ds_read_b32 v0, v0
	s_cbranch_vccnz .LBB0_563
	s_load_dwordx2 s[2:3], s[64:65], 0x0
	s_load_dword s4, s[64:65], 0x8
	s_mov_b32 s10, 1
	s_waitcnt lgkmcnt(0)
	s_mul_i32 s9, s3, s2
	s_mul_i32 s9, s9, s4
	s_branch .LBB0_551

; __device__ __forceinline__ unsigned xb_ld(unsigned* p)              { return __hip_atomic_load(p, __ATOMIC_RELAXED, __HIP_MEMORY_SCOPE_AGENT); }
; __device__ __forceinline__ unsigned xb_add(unsigned* p, unsigned v) { return __hip_atomic_fetch_add(p, v, __ATOMIC_RELAXED, __HIP_MEMORY_SCOPE_AGENT); }
; #define XB_SPIN(cond, bar) do { unsigned _sp = 0; while (cond) { __builtin_amdgcn_s_sleep(1); \
;     if ((++_sp & 255u) == 0u) { if (xb_ld(&(bar)[XB_TMO])) break; if (_sp > XB_SPIN_CAP) { atomicAdd(&(bar)[XB_TMO], 1u); break; } } } } while (0)
; __device__ __forceinline__ void xcd_barrier(const XcdBarrier& b) {
;     asm volatile("s_waitcnt vmcnt(0)" ::: "memory");
;     __syncthreads();
;     if (threadIdx.x == 0) {
;         unsigned* bar = b.bar;
;         unsigned bx = b.x; asm volatile("" : "+s"(bx));
;         __builtin_amdgcn_s_waitcnt(0);
;         unsigned nloc = b.st[0], nx = b.st[1];
;         if (nloc == 0u) { xcd_barrier_complete(bar, bx, nloc, nx); b.st[0] = nloc; b.st[1] = nx; }
;         const unsigned old = xb_add(&bar[XB_XSUB(bx)], 1u);
;         const unsigned gen = old / nloc;
;         if (old + 1u == (gen + 1u) * nloc) {
;             __builtin_amdgcn_fence(__ATOMIC_RELEASE, "agent");
;             asm volatile("s_waitcnt vmcnt(0)" ::: "memory");
;             const unsigned og = xb_add(&bar[XB_TOP], 1u);
;             const unsigned tg = og / nx;
;             if (og + 1u == (tg + 1u) * nx) xb_add(&bar[XB_TOPGEN], 1u);
;             else XB_SPIN(xb_ld(&bar[XB_TOPGEN]) == tg, bar);
;             __builtin_amdgcn_fence(__ATOMIC_ACQUIRE, "agent");
;             xb_add(&bar[XB_XGEN(bx)], 1u);
;             asm volatile("s_waitcnt vmcnt(0)" ::: "memory");
;         } else {
;             XB_SPIN(xb_ld(&bar[XB_XGEN(bx)]) == gen, bar);
; __global__ void __launch_bounds__(NTHREADS) fwd_megakernel(Params p) {
;     ...
;         xcd_barrier(gb);
.LBB0_676:
	s_mov_b64 s[0:1], -1
	s_and_b64 vcc, exec, s[2:3]
	s_mov_b64 s[2:3], -1
	s_cbranch_vccz .LBB0_102
	s_waitcnt vmcnt(0)
	s_waitcnt lgkmcnt(0)
	s_barrier
	s_and_saveexec_b64 s[0:1], s[66:67]
	s_cbranch_execz .LBB0_101
	s_cmp_eq_u32 s99, 0
	s_cbranch_scc1 .Lxb_full_3
	v_readlane_b32 s2, v254, 2
	v_mov_b32_e32 v1, 1
	s_lshl_b32 s2, s2, 8
	s_mov_b32 s98, 0
	v_mov_b32_e32 v0, s2
	global_atomic_add v1, v0, v1, s[82:83] offset:1152 sc0
	s_waitcnt vmcnt(0)
	v_lshrrev_b32_e32 v1, 5, v1
	v_add_u32_e32 v1, 1, v1
	v_lshlrev_b32_e32 v1, 5, v1

; __device__ __forceinline__ unsigned xb_ld(unsigned* p)              { return __hip_atomic_load(p, __ATOMIC_RELAXED, __HIP_MEMORY_SCOPE_AGENT); }
; __device__ __forceinline__ unsigned xb_add(unsigned* p, unsigned v) { return __hip_atomic_fetch_add(p, v, __ATOMIC_RELAXED, __HIP_MEMORY_SCOPE_AGENT); }
; #define XB_SPIN(cond, bar) do { unsigned _sp = 0; while (cond) { __builtin_amdgcn_s_sleep(1); \
;     if ((++_sp & 255u) == 0u) { if (xb_ld(&(bar)[XB_TMO])) break; if (_sp > XB_SPIN_CAP) { atomicAdd(&(bar)[XB_TMO], 1u); break; } } } } while (0)
; __device__ __forceinline__ void xcd_barrier(const XcdBarrier& b) {
;     ...
;     if (threadIdx.x == 0) {
;         unsigned* bar = b.bar;
;         unsigned bx = b.x; asm volatile("" : "+s"(bx));
;         __builtin_amdgcn_s_waitcnt(0);
;         unsigned nloc = b.st[0], nx = b.st[1];
;         if (nloc == 0u) { xcd_barrier_complete(bar, bx, nloc, nx); b.st[0] = nloc; b.st[1] = nx; }
;         const unsigned old = xb_add(&bar[XB_XSUB(bx)], 1u);
;         const unsigned gen = old / nloc;
;         if (old + 1u == (gen + 1u) * nloc) {
;             __builtin_amdgcn_fence(__ATOMIC_RELEASE, "agent");
;             asm volatile("s_waitcnt vmcnt(0)" ::: "memory");
;             const unsigned og = xb_add(&bar[XB_TOP], 1u);
;             const unsigned tg = og / nx;
;             if (og + 1u == (tg + 1u) * nx) xb_add(&bar[XB_TOPGEN], 1u);
;             else XB_SPIN(xb_ld(&bar[XB_TOPGEN]) == tg, bar);
.Lxb_full_3:
	v_readlane_b32 s2, v254, 46
	v_readlane_b32 s8, v254, 2
	s_waitcnt vmcnt(0) expcnt(0) lgkmcnt(0)
	v_mov_b32_e32 v0, s2
	ds_read_b32 v2, v0
	v_readlane_b32 s2, v254, 47
	s_waitcnt lgkmcnt(0)
	v_cmp_ne_u32_e32 vcc, 0, v2
	v_mov_b32_e32 v0, s2
	ds_read_b32 v0, v0
	s_cbranch_vccnz .LBB0_693
	s_load_dwordx2 s[2:3], s[64:65], 0x4
	s_mov_b32 s10, 1
	s_waitcnt lgkmcnt(0)
	s_mul_i32 s9, s2, s22
	s_mul_i32 s9, s9, s3
	s_branch .LBB0_681

; __global__ void __launch_bounds__(NTHREADS) fwd_megakernel(Params p) {
	.amdhsa_kernel _Z14fwd_megakernel6Params
		.amdhsa_group_segment_fixed_size 0
		.amdhsa_private_segment_fixed_size 0
		.amdhsa_kernarg_size 440
		.amdhsa_user_sgpr_count 2
		.amdhsa_user_sgpr_dispatch_ptr 0
		.amdhsa_user_sgpr_queue_ptr 0
		.amdhsa_user_sgpr_kernarg_segment_ptr 1
		.amdhsa_user_sgpr_dispatch_id 0
		.amdhsa_user_sgpr_kernarg_preload_length 0
		.amdhsa_user_sgpr_kernarg_preload_offset 0
		.amdhsa_user_sgpr_private_segment_size 0
		.amdhsa_uses_dynamic_stack 0
		.amdhsa_enable_private_segment 0
		.amdhsa_system_sgpr_workgroup_id_x 1
		.amdhsa_system_sgpr_workgroup_id_y 0
		.amdhsa_system_sgpr_workgroup_id_z 0
		.amdhsa_system_sgpr_workgroup_info 0
		.amdhsa_system_vgpr_workitem_id 2
		.amdhsa_next_free_vgpr 256
		.amdhsa_next_free_sgpr 102
		.amdhsa_accum_offset 256
		.amdhsa_reserve_vcc 1
		.amdhsa_float_round_mode_32 0
		.amdhsa_float_round_mode_16_64 0
		.amdhsa_float_denorm_mode_32 3
		.amdhsa_float_denorm_mode_16_64 3
		.amdhsa_dx10_clamp 1
		.amdhsa_ieee_mode 1
		.amdhsa_fp16_overflow 0
		.amdhsa_tg_split 0
		.amdhsa_exception_fp_ieee_invalid_op 0
		.amdhsa_exception_fp_denorm_src 0
		.amdhsa_exception_fp_ieee_div_zero 0
		.amdhsa_exception_fp_ieee_overflow 0
		.amdhsa_exception_fp_ieee_underflow 0
		.amdhsa_exception_fp_ieee_inexact 0
		.amdhsa_exception_int_div_zero 0
	.end_amdhsa_kernel

; __global__ void __launch_bounds__(NTHREADS) fwd_megakernel(Params p) {
amdhsa.kernels:
  - .agpr_count:     0
    .args:
      - .offset:         0
        .size:           184
        .value_kind:     by_value
      - .offset:         184
        .size:           4
        .value_kind:     hidden_block_count_x
      - .offset:         188
        .size:           4
        .value_kind:     hidden_block_count_y
      - .offset:         192
        .size:           4
        .value_kind:     hidden_block_count_z
      - .offset:         196
        .size:           2
        .value_kind:     hidden_group_size_x
      - .offset:         198
        .size:           2
        .value_kind:     hidden_group_size_y
      - .offset:         200
        .size:           2
        .value_kind:     hidden_group_size_z
      - .offset:         202
        .size:           2
        .value_kind:     hidden_remainder_x
      - .offset:         204
        .size:           2
        .value_kind:     hidden_remainder_y
      - .offset:         206
        .size:           2
        .value_kind:     hidden_remainder_z
      - .offset:         224
        .size:           8
        .value_kind:     hidden_global_offset_x
      - .offset:         232
        .size:           8
        .value_kind:     hidden_global_offset_y
      - .offset:         240
        .size:           8
        .value_kind:     hidden_global_offset_z
      - .offset:         248
        .size:           2
        .value_kind:     hidden_grid_dims
      - .offset:         272
        .size:           8
        .value_kind:     hidden_multigrid_sync_arg
      - .offset:         304
        .size:           4
        .value_kind:     hidden_dynamic_lds_size
    .group_segment_fixed_size: 0
    .kernarg_segment_align: 8
    .kernarg_segment_size: 440
    .language:       OpenCL C
    .language_version:
      - 2
      - 0
    .max_flat_workgroup_size: 512
    .name:           _Z14fwd_megakernel6Params
    .private_segment_fixed_size: 0
    .sgpr_count:     108
    .sgpr_spill_count: 109
    .symbol:         _Z14fwd_megakernel6Params.kd
    .uniform_work_group_size: 1
    .uses_dynamic_stack: false
    .vgpr_count:     256
    .vgpr_spill_count: 0
    .wavefront_size: 64
